# v5 + attention epilogue lane-pair exchange by DPP quad_perm instead of ds_bpermute
# speedup vs baseline: 1.0278x; 1.0065x over previous
.LBB0_954:
	s_or_b64 exec, exec, s[4:5]
	s_waitcnt lgkmcnt(0)
	ds_read_b128 v[76:79], v201
	ds_read_b128 v[72:75], v201 offset:32
	v_and_b32_e32 v81, 64, v190
	v_xor_b32_e32 v80, 1, v190
	v_add_u32_e32 v81, 64, v81
	s_waitcnt lgkmcnt(1)
	v_rcp_f32_e32 v76, v76
	v_cmp_lt_i32_e32 vcc, v80, v81
	ds_read_b128 v[68:71], v201 offset:64
	ds_read_b128 v[64:67], v201 offset:96
	v_cndmask_b32_e32 v80, v190, v80, vcc
	v_lshlrev_b32_e32 v170, 2, v80
	v_mul_f32_e32 v48, v48, v76
	s_nop 1
	v_mov_b32_dpp v84, v48 quad_perm:[1,0,3,2] row_mask:0xf bank_mask:0xf
	s_add_u32 s0, s90, s8
	s_addc_u32 s1, s91, s9
	v_and_b32_e32 v80, 1, v181
	v_lshlrev_b32_e32 v130, 1, v197
	v_ashrrev_i32_e32 v181, 31, v180
	v_cmp_eq_u32_e32 vcc, 0, v80
	v_lshl_add_u64 v[80:81], s[0:1], 0, v[130:131]
	v_lshlrev_b64 v[82:83], 12, v[180:181]
	v_lshl_add_u64 v[82:83], v[80:81], 0, v[82:83]
	s_and_saveexec_b64 s[4:5], vcc
	s_cbranch_execz .LBB0_956
	s_waitcnt lgkmcnt(0)
	v_cvt_pk_bf16_f32 v48, v48, v84
	global_store_dword v[82:83], v48, off
.LBB0_956:
	s_or_b64 exec, exec, s[4:5]
	v_mul_f32_e32 v32, v32, v76
	s_nop 1
	v_mov_b32_dpp v48, v32 quad_perm:[1,0,3,2] row_mask:0xf bank_mask:0xf
	s_and_saveexec_b64 s[4:5], vcc
	s_cbranch_execz .LBB0_958
	s_waitcnt lgkmcnt(0)
	v_cvt_pk_bf16_f32 v32, v32, v48
	global_store_dword v[82:83], v32, off offset:64
.LBB0_958:
	s_or_b64 exec, exec, s[4:5]
	v_mul_f32_e32 v16, v16, v76
	s_nop 1
	v_mov_b32_dpp v32, v16 quad_perm:[1,0,3,2] row_mask:0xf bank_mask:0xf
	s_and_saveexec_b64 s[4:5], vcc
	s_cbranch_execz .LBB0_960
	s_waitcnt lgkmcnt(0)
	v_cvt_pk_bf16_f32 v16, v16, v32
	global_store_dword v[82:83], v16, off offset:128
.LBB0_960:
	s_or_b64 exec, exec, s[4:5]
	v_mul_f32_e32 v0, v0, v76
	s_nop 1
	v_mov_b32_dpp v16, v0 quad_perm:[1,0,3,2] row_mask:0xf bank_mask:0xf
	s_and_saveexec_b64 s[4:5], vcc
	s_cbranch_execz .LBB0_962
	s_waitcnt lgkmcnt(0)
	v_cvt_pk_bf16_f32 v0, v0, v16
	global_store_dword v[82:83], v0, off offset:192
.LBB0_962:
	s_or_b64 exec, exec, s[4:5]
	v_rcp_f32_e32 v0, v77
	v_or_b32_e32 v76, 1, v180
	v_ashrrev_i32_e32 v77, 31, v76
	v_lshlrev_b64 v[76:77], 12, v[76:77]
	s_waitcnt lgkmcnt(0)
	v_mul_f32_e32 v16, v49, v0
	s_nop 1
	v_mov_b32_dpp v32, v16 quad_perm:[1,0,3,2] row_mask:0xf bank_mask:0xf
	v_lshl_add_u64 v[76:77], v[80:81], 0, v[76:77]
	s_and_saveexec_b64 s[4:5], vcc
	s_cbranch_execz .LBB0_964
	s_waitcnt lgkmcnt(0)
	v_cvt_pk_bf16_f32 v16, v16, v32
	global_store_dword v[76:77], v16, off
.LBB0_964:
	s_or_b64 exec, exec, s[4:5]
	v_mul_f32_e32 v16, v33, v0
	s_waitcnt lgkmcnt(0)
	s_nop 1
	v_mov_b32_dpp v32, v16 quad_perm:[1,0,3,2] row_mask:0xf bank_mask:0xf
	s_and_saveexec_b64 s[4:5], vcc
	s_cbranch_execz .LBB0_966
	s_waitcnt lgkmcnt(0)
	v_cvt_pk_bf16_f32 v16, v16, v32
	global_store_dword v[76:77], v16, off offset:64
.LBB0_966:
	s_or_b64 exec, exec, s[4:5]
	v_mul_f32_e32 v16, v17, v0
	s_nop 1
	v_mov_b32_dpp v17, v16 quad_perm:[1,0,3,2] row_mask:0xf bank_mask:0xf
	s_and_saveexec_b64 s[4:5], vcc
	s_cbranch_execz .LBB0_968
	s_waitcnt lgkmcnt(0)
	v_cvt_pk_bf16_f32 v16, v16, v17
	global_store_dword v[76:77], v16, off offset:128
.LBB0_968:
	s_or_b64 exec, exec, s[4:5]
	v_mul_f32_e32 v0, v1, v0
	s_nop 1
	v_mov_b32_dpp v1, v0 quad_perm:[1,0,3,2] row_mask:0xf bank_mask:0xf
	s_and_saveexec_b64 s[4:5], vcc
	s_cbranch_execz .LBB0_970
	s_waitcnt lgkmcnt(0)
	v_cvt_pk_bf16_f32 v0, v0, v1
	global_store_dword v[76:77], v0, off offset:192
.LBB0_970:
	s_or_b64 exec, exec, s[4:5]
	v_rcp_f32_e32 v16, v78
	v_or_b32_e32 v0, 2, v180
	s_waitcnt lgkmcnt(0)
	v_ashrrev_i32_e32 v1, 31, v0
	v_lshlrev_b64 v[0:1], 12, v[0:1]
	v_mul_f32_e32 v17, v50, v16
	s_nop 1
	v_mov_b32_dpp v32, v17 quad_perm:[1,0,3,2] row_mask:0xf bank_mask:0xf
	v_lshl_add_u64 v[0:1], v[80:81], 0, v[0:1]
	s_and_saveexec_b64 s[4:5], vcc
	s_cbranch_execz .LBB0_972
	s_waitcnt lgkmcnt(0)
	v_cvt_pk_bf16_f32 v17, v17, v32
	global_store_dword v[0:1], v17, off
.LBB0_972:
	s_or_b64 exec, exec, s[4:5]
	v_mul_f32_e32 v17, v34, v16
	s_waitcnt lgkmcnt(0)
	s_nop 1
	v_mov_b32_dpp v32, v17 quad_perm:[1,0,3,2] row_mask:0xf bank_mask:0xf
	s_and_saveexec_b64 s[4:5], vcc
	s_cbranch_execz .LBB0_974
	s_waitcnt lgkmcnt(0)
	v_cvt_pk_bf16_f32 v17, v17, v32
	global_store_dword v[0:1], v17, off offset:64
.LBB0_974:
	s_or_b64 exec, exec, s[4:5]
	v_mul_f32_e32 v17, v18, v16
	s_nop 1
	v_mov_b32_dpp v18, v17 quad_perm:[1,0,3,2] row_mask:0xf bank_mask:0xf
	s_and_saveexec_b64 s[4:5], vcc
	s_cbranch_execz .LBB0_976
	s_waitcnt lgkmcnt(0)
	v_cvt_pk_bf16_f32 v17, v17, v18
	global_store_dword v[0:1], v17, off offset:128
.LBB0_976:
	s_or_b64 exec, exec, s[4:5]
	v_mul_f32_e32 v2, v2, v16
	s_nop 1
	v_mov_b32_dpp v16, v2 quad_perm:[1,0,3,2] row_mask:0xf bank_mask:0xf
	s_and_saveexec_b64 s[4:5], vcc
	s_cbranch_execz .LBB0_978
	s_waitcnt lgkmcnt(0)
	v_cvt_pk_bf16_f32 v2, v2, v16
	global_store_dword v[0:1], v2, off offset:192
.LBB0_978:
	s_or_b64 exec, exec, s[4:5]
	v_rcp_f32_e32 v2, v79
	v_or_b32_e32 v0, 3, v180
	v_ashrrev_i32_e32 v1, 31, v0
	v_lshlrev_b64 v[0:1], 12, v[0:1]
	s_waitcnt lgkmcnt(0)
	v_mul_f32_e32 v16, v51, v2
	s_nop 1
	v_mov_b32_dpp v17, v16 quad_perm:[1,0,3,2] row_mask:0xf bank_mask:0xf
	v_lshl_add_u64 v[0:1], v[80:81], 0, v[0:1]
	s_and_saveexec_b64 s[4:5], vcc
	s_cbranch_execz .LBB0_980
	s_waitcnt lgkmcnt(0)
	v_cvt_pk_bf16_f32 v16, v16, v17
	global_store_dword v[0:1], v16, off
.LBB0_980:
	s_or_b64 exec, exec, s[4:5]
	v_mul_f32_e32 v16, v35, v2
	s_waitcnt lgkmcnt(0)
	s_nop 1
	v_mov_b32_dpp v17, v16 quad_perm:[1,0,3,2] row_mask:0xf bank_mask:0xf
	s_and_saveexec_b64 s[4:5], vcc
	s_cbranch_execz .LBB0_982
	s_waitcnt lgkmcnt(0)
	v_cvt_pk_bf16_f32 v16, v16, v17
	global_store_dword v[0:1], v16, off offset:64
.LBB0_982:
	s_or_b64 exec, exec, s[4:5]
	v_mul_f32_e32 v16, v19, v2
	s_waitcnt lgkmcnt(0)
	s_nop 1
	v_mov_b32_dpp v17, v16 quad_perm:[1,0,3,2] row_mask:0xf bank_mask:0xf
	s_and_saveexec_b64 s[4:5], vcc
	s_cbranch_execz .LBB0_984
	s_waitcnt lgkmcnt(0)
	v_cvt_pk_bf16_f32 v16, v16, v17
	global_store_dword v[0:1], v16, off offset:128
.LBB0_984:
	s_or_b64 exec, exec, s[4:5]
	v_mul_f32_e32 v2, v3, v2
	s_nop 1
	v_mov_b32_dpp v3, v2 quad_perm:[1,0,3,2] row_mask:0xf bank_mask:0xf
	s_and_saveexec_b64 s[4:5], vcc
	s_cbranch_execz .LBB0_986
	s_waitcnt lgkmcnt(0)
	v_cvt_pk_bf16_f32 v2, v2, v3
	global_store_dword v[0:1], v2, off offset:192
.LBB0_986:
	s_or_b64 exec, exec, s[4:5]
	v_rcp_f32_e32 v2, v72
	v_lshlrev_b64 v[0:1], 12, v[180:181]
	v_lshl_add_u64 v[0:1], v[80:81], 0, v[0:1]
	v_lshl_add_u64 v[0:1], v[0:1], 0, s[34:35]
	s_waitcnt lgkmcnt(0)
	v_mul_f32_e32 v3, v52, v2
	s_nop 1
	v_mov_b32_dpp v16, v3 quad_perm:[1,0,3,2] row_mask:0xf bank_mask:0xf
	s_and_saveexec_b64 s[4:5], vcc
	s_cbranch_execz .LBB0_988
	s_waitcnt lgkmcnt(0)
	v_cvt_pk_bf16_f32 v3, v3, v16
	global_store_dword v[0:1], v3, off
.LBB0_988:
	s_or_b64 exec, exec, s[4:5]
	v_mul_f32_e32 v3, v36, v2
	s_waitcnt lgkmcnt(0)
	s_nop 1
	v_mov_b32_dpp v16, v3 quad_perm:[1,0,3,2] row_mask:0xf bank_mask:0xf
	s_and_saveexec_b64 s[4:5], vcc
	s_cbranch_execz .LBB0_990
	s_waitcnt lgkmcnt(0)
	v_cvt_pk_bf16_f32 v3, v3, v16
	global_store_dword v[0:1], v3, off offset:64
.LBB0_990:
	s_or_b64 exec, exec, s[4:5]
	v_mul_f32_e32 v3, v20, v2
	s_waitcnt lgkmcnt(0)
	s_nop 1
	v_mov_b32_dpp v16, v3 quad_perm:[1,0,3,2] row_mask:0xf bank_mask:0xf
	s_and_saveexec_b64 s[4:5], vcc
	s_cbranch_execz .LBB0_992
	s_waitcnt lgkmcnt(0)
	v_cvt_pk_bf16_f32 v3, v3, v16
	global_store_dword v[0:1], v3, off offset:128
.LBB0_992:
	s_or_b64 exec, exec, s[4:5]
	v_mul_f32_e32 v2, v4, v2
	s_nop 1
	v_mov_b32_dpp v3, v2 quad_perm:[1,0,3,2] row_mask:0xf bank_mask:0xf
	s_and_saveexec_b64 s[4:5], vcc
	s_cbranch_execz .LBB0_994
	s_waitcnt lgkmcnt(0)
	v_cvt_pk_bf16_f32 v2, v2, v3
	global_store_dword v[0:1], v2, off offset:192
.LBB0_994:
	s_or_b64 exec, exec, s[4:5]
	v_rcp_f32_e32 v2, v73
	v_lshlrev_b64 v[0:1], 12, v[180:181]
	v_lshl_add_u64 v[0:1], v[80:81], 0, v[0:1]
	v_lshl_add_u64 v[0:1], v[0:1], 0, s[48:49]
	s_waitcnt lgkmcnt(0)
	v_mul_f32_e32 v3, v53, v2
	s_nop 1
	v_mov_b32_dpp v4, v3 quad_perm:[1,0,3,2] row_mask:0xf bank_mask:0xf
	s_and_saveexec_b64 s[4:5], vcc
	s_cbranch_execz .LBB0_996
	s_waitcnt lgkmcnt(0)
	v_cvt_pk_bf16_f32 v3, v3, v4
	global_store_dword v[0:1], v3, off
.LBB0_996:
	s_or_b64 exec, exec, s[4:5]
	v_mul_f32_e32 v3, v37, v2
	s_waitcnt lgkmcnt(0)
	s_nop 1
	v_mov_b32_dpp v4, v3 quad_perm:[1,0,3,2] row_mask:0xf bank_mask:0xf
	s_and_saveexec_b64 s[4:5], vcc
	s_cbranch_execz .LBB0_998
	s_waitcnt lgkmcnt(0)
	v_cvt_pk_bf16_f32 v3, v3, v4
	global_store_dword v[0:1], v3, off offset:64
.LBB0_998:
	s_or_b64 exec, exec, s[4:5]
	v_mul_f32_e32 v3, v21, v2
	s_waitcnt lgkmcnt(0)
	s_nop 1
	v_mov_b32_dpp v4, v3 quad_perm:[1,0,3,2] row_mask:0xf bank_mask:0xf
	s_and_saveexec_b64 s[4:5], vcc
	s_cbranch_execz .LBB0_1000
	s_waitcnt lgkmcnt(0)
	v_cvt_pk_bf16_f32 v3, v3, v4
	global_store_dword v[0:1], v3, off offset:128
.LBB0_1000:
	s_or_b64 exec, exec, s[4:5]
	v_mul_f32_e32 v2, v5, v2
	s_nop 1
	v_mov_b32_dpp v3, v2 quad_perm:[1,0,3,2] row_mask:0xf bank_mask:0xf
	s_and_saveexec_b64 s[4:5], vcc
	s_cbranch_execz .LBB0_1002
	s_waitcnt lgkmcnt(0)
	v_cvt_pk_bf16_f32 v2, v2, v3
	global_store_dword v[0:1], v2, off offset:192
.LBB0_1002:
	s_or_b64 exec, exec, s[4:5]
	v_rcp_f32_e32 v2, v74
	v_lshlrev_b64 v[0:1], 12, v[180:181]
	v_lshl_add_u64 v[0:1], v[80:81], 0, v[0:1]
	v_lshl_add_u64 v[0:1], v[0:1], 0, s[54:55]
	s_waitcnt lgkmcnt(0)
	v_mul_f32_e32 v3, v54, v2
	s_nop 1
	v_mov_b32_dpp v4, v3 quad_perm:[1,0,3,2] row_mask:0xf bank_mask:0xf
	s_and_saveexec_b64 s[4:5], vcc
	s_cbranch_execz .LBB0_1004
	s_waitcnt lgkmcnt(0)
	v_cvt_pk_bf16_f32 v3, v3, v4
	global_store_dword v[0:1], v3, off
.LBB0_1004:
	s_or_b64 exec, exec, s[4:5]
	v_mul_f32_e32 v3, v38, v2
	s_waitcnt lgkmcnt(0)
	s_nop 1
	v_mov_b32_dpp v4, v3 quad_perm:[1,0,3,2] row_mask:0xf bank_mask:0xf
	s_and_saveexec_b64 s[4:5], vcc
	s_cbranch_execz .LBB0_1006
	s_waitcnt lgkmcnt(0)
	v_cvt_pk_bf16_f32 v3, v3, v4
	global_store_dword v[0:1], v3, off offset:64
.LBB0_1006:
	s_or_b64 exec, exec, s[4:5]
	v_mul_f32_e32 v3, v22, v2
	s_waitcnt lgkmcnt(0)
	s_nop 1
	v_mov_b32_dpp v4, v3 quad_perm:[1,0,3,2] row_mask:0xf bank_mask:0xf
	s_and_saveexec_b64 s[4:5], vcc
	s_cbranch_execz .LBB0_1008
	s_waitcnt lgkmcnt(0)
	v_cvt_pk_bf16_f32 v3, v3, v4
	global_store_dword v[0:1], v3, off offset:128
.LBB0_1008:
	s_or_b64 exec, exec, s[4:5]
	v_mul_f32_e32 v2, v6, v2
	s_nop 1
	v_mov_b32_dpp v3, v2 quad_perm:[1,0,3,2] row_mask:0xf bank_mask:0xf
	s_and_saveexec_b64 s[4:5], vcc
	s_cbranch_execz .LBB0_1010
	s_waitcnt lgkmcnt(0)
	v_cvt_pk_bf16_f32 v2, v2, v3
	global_store_dword v[0:1], v2, off offset:192
.LBB0_1010:
	s_or_b64 exec, exec, s[4:5]
	v_rcp_f32_e32 v2, v75
	v_lshlrev_b64 v[0:1], 12, v[180:181]
	v_lshl_add_u64 v[0:1], v[80:81], 0, v[0:1]
	v_lshl_add_u64 v[0:1], v[0:1], 0, s[40:41]
	s_waitcnt lgkmcnt(0)
	v_mul_f32_e32 v3, v55, v2
	s_nop 1
	v_mov_b32_dpp v4, v3 quad_perm:[1,0,3,2] row_mask:0xf bank_mask:0xf
	s_and_saveexec_b64 s[4:5], vcc
	s_cbranch_execz .LBB0_1012
	s_waitcnt lgkmcnt(0)
	v_cvt_pk_bf16_f32 v3, v3, v4
	global_store_dword v[0:1], v3, off
.LBB0_1012:
	s_or_b64 exec, exec, s[4:5]
	v_mul_f32_e32 v3, v39, v2
	s_waitcnt lgkmcnt(0)
	s_nop 1
	v_mov_b32_dpp v4, v3 quad_perm:[1,0,3,2] row_mask:0xf bank_mask:0xf
	s_and_saveexec_b64 s[4:5], vcc
	s_cbranch_execz .LBB0_1014
	s_waitcnt lgkmcnt(0)
	v_cvt_pk_bf16_f32 v3, v3, v4
	global_store_dword v[0:1], v3, off offset:64
.LBB0_1014:
	s_or_b64 exec, exec, s[4:5]
	v_mul_f32_e32 v3, v23, v2
	s_waitcnt lgkmcnt(0)
	s_nop 1
	v_mov_b32_dpp v4, v3 quad_perm:[1,0,3,2] row_mask:0xf bank_mask:0xf
	s_and_saveexec_b64 s[4:5], vcc
	s_cbranch_execz .LBB0_1016
	s_waitcnt lgkmcnt(0)
	v_cvt_pk_bf16_f32 v3, v3, v4
	global_store_dword v[0:1], v3, off offset:128
.LBB0_1016:
	s_or_b64 exec, exec, s[4:5]
	v_mul_f32_e32 v2, v7, v2
	s_nop 1
	v_mov_b32_dpp v3, v2 quad_perm:[1,0,3,2] row_mask:0xf bank_mask:0xf
	s_and_saveexec_b64 s[4:5], vcc
	s_cbranch_execz .LBB0_1018
	s_waitcnt lgkmcnt(0)
	v_cvt_pk_bf16_f32 v2, v2, v3
	global_store_dword v[0:1], v2, off offset:192
.LBB0_1018:
	s_or_b64 exec, exec, s[4:5]
	v_rcp_f32_e32 v2, v68
	v_lshlrev_b64 v[0:1], 12, v[180:181]
	v_lshl_add_u64 v[0:1], v[80:81], 0, v[0:1]
	s_mov_b64 s[0:1], 0x10000
	s_waitcnt lgkmcnt(0)
	v_mul_f32_e32 v3, v56, v2
	s_nop 1
	v_mov_b32_dpp v4, v3 quad_perm:[1,0,3,2] row_mask:0xf bank_mask:0xf
	v_lshl_add_u64 v[0:1], v[0:1], 0, s[0:1]
	s_and_saveexec_b64 s[4:5], vcc
	s_cbranch_execz .LBB0_1020
	s_waitcnt lgkmcnt(0)
	v_cvt_pk_bf16_f32 v3, v3, v4
	global_store_dword v[0:1], v3, off
.LBB0_1020:
	s_or_b64 exec, exec, s[4:5]
	v_mul_f32_e32 v3, v40, v2
	s_waitcnt lgkmcnt(0)
	s_nop 1
	v_mov_b32_dpp v4, v3 quad_perm:[1,0,3,2] row_mask:0xf bank_mask:0xf
	s_and_saveexec_b64 s[4:5], vcc
	s_cbranch_execz .LBB0_1022
	s_waitcnt lgkmcnt(0)
	v_cvt_pk_bf16_f32 v3, v3, v4
	global_store_dword v[0:1], v3, off offset:64
.LBB0_1022:
	s_or_b64 exec, exec, s[4:5]
	v_mul_f32_e32 v3, v24, v2
	s_waitcnt lgkmcnt(0)
	s_nop 1
	v_mov_b32_dpp v4, v3 quad_perm:[1,0,3,2] row_mask:0xf bank_mask:0xf
	s_and_saveexec_b64 s[4:5], vcc
	s_cbranch_execz .LBB0_1024
	s_waitcnt lgkmcnt(0)
	v_cvt_pk_bf16_f32 v3, v3, v4
	global_store_dword v[0:1], v3, off offset:128
.LBB0_1024:
	s_or_b64 exec, exec, s[4:5]
	v_mul_f32_e32 v2, v8, v2
	s_nop 1
	v_mov_b32_dpp v3, v2 quad_perm:[1,0,3,2] row_mask:0xf bank_mask:0xf
	s_and_saveexec_b64 s[4:5], vcc
	s_cbranch_execz .LBB0_1026
	s_waitcnt lgkmcnt(0)
	v_cvt_pk_bf16_f32 v2, v2, v3
	global_store_dword v[0:1], v2, off offset:192
.LBB0_1026:
	s_or_b64 exec, exec, s[4:5]
	v_rcp_f32_e32 v2, v69
	v_lshlrev_b64 v[0:1], 12, v[180:181]
	v_lshl_add_u64 v[0:1], v[80:81], 0, v[0:1]
	s_mov_b64 s[0:1], 0x11000
	s_waitcnt lgkmcnt(0)
	v_mul_f32_e32 v3, v57, v2
	s_nop 1
	v_mov_b32_dpp v4, v3 quad_perm:[1,0,3,2] row_mask:0xf bank_mask:0xf
	v_lshl_add_u64 v[0:1], v[0:1], 0, s[0:1]
	s_and_saveexec_b64 s[4:5], vcc
	s_cbranch_execz .LBB0_1028
	s_waitcnt lgkmcnt(0)
	v_cvt_pk_bf16_f32 v3, v3, v4
	global_store_dword v[0:1], v3, off
.LBB0_1028:
	s_or_b64 exec, exec, s[4:5]
	v_mul_f32_e32 v3, v41, v2
	s_waitcnt lgkmcnt(0)
	s_nop 1
	v_mov_b32_dpp v4, v3 quad_perm:[1,0,3,2] row_mask:0xf bank_mask:0xf
	s_and_saveexec_b64 s[4:5], vcc
	s_cbranch_execz .LBB0_1030
	s_waitcnt lgkmcnt(0)
	v_cvt_pk_bf16_f32 v3, v3, v4
	global_store_dword v[0:1], v3, off offset:64
.LBB0_1030:
	s_or_b64 exec, exec, s[4:5]
	v_mul_f32_e32 v3, v25, v2
	s_waitcnt lgkmcnt(0)
	s_nop 1
	v_mov_b32_dpp v4, v3 quad_perm:[1,0,3,2] row_mask:0xf bank_mask:0xf
	s_and_saveexec_b64 s[4:5], vcc
	s_cbranch_execz .LBB0_1032
	s_waitcnt lgkmcnt(0)
	v_cvt_pk_bf16_f32 v3, v3, v4
	global_store_dword v[0:1], v3, off offset:128
.LBB0_1032:
	s_or_b64 exec, exec, s[4:5]
	v_mul_f32_e32 v2, v9, v2
	s_nop 1
	v_mov_b32_dpp v3, v2 quad_perm:[1,0,3,2] row_mask:0xf bank_mask:0xf
	s_and_saveexec_b64 s[4:5], vcc
	s_cbranch_execz .LBB0_1034
	s_waitcnt lgkmcnt(0)
	v_cvt_pk_bf16_f32 v2, v2, v3
	global_store_dword v[0:1], v2, off offset:192
.LBB0_1034:
	s_or_b64 exec, exec, s[4:5]
	v_rcp_f32_e32 v2, v70
	v_lshlrev_b64 v[0:1], 12, v[180:181]
	v_lshl_add_u64 v[0:1], v[80:81], 0, v[0:1]
	v_lshl_add_u64 v[0:1], v[0:1], 0, s[56:57]
	s_waitcnt lgkmcnt(0)
	v_mul_f32_e32 v3, v58, v2
	s_nop 1
	v_mov_b32_dpp v4, v3 quad_perm:[1,0,3,2] row_mask:0xf bank_mask:0xf
	s_and_saveexec_b64 s[4:5], vcc
	s_cbranch_execz .LBB0_1036
	s_waitcnt lgkmcnt(0)
	v_cvt_pk_bf16_f32 v3, v3, v4
	global_store_dword v[0:1], v3, off
.LBB0_1036:
	s_or_b64 exec, exec, s[4:5]
	v_mul_f32_e32 v3, v42, v2
	s_waitcnt lgkmcnt(0)
	s_nop 1
	v_mov_b32_dpp v4, v3 quad_perm:[1,0,3,2] row_mask:0xf bank_mask:0xf
	s_and_saveexec_b64 s[4:5], vcc
	s_cbranch_execz .LBB0_1038
	s_waitcnt lgkmcnt(0)
	v_cvt_pk_bf16_f32 v3, v3, v4
	global_store_dword v[0:1], v3, off offset:64
.LBB0_1038:
	s_or_b64 exec, exec, s[4:5]
	v_mul_f32_e32 v3, v26, v2
	s_waitcnt lgkmcnt(0)
	s_nop 1
	v_mov_b32_dpp v4, v3 quad_perm:[1,0,3,2] row_mask:0xf bank_mask:0xf
	s_and_saveexec_b64 s[4:5], vcc
	s_cbranch_execz .LBB0_1040
	s_waitcnt lgkmcnt(0)
	v_cvt_pk_bf16_f32 v3, v3, v4
	global_store_dword v[0:1], v3, off offset:128
.LBB0_1040:
	s_or_b64 exec, exec, s[4:5]
	v_mul_f32_e32 v2, v10, v2
	s_nop 1
	v_mov_b32_dpp v3, v2 quad_perm:[1,0,3,2] row_mask:0xf bank_mask:0xf
	s_and_saveexec_b64 s[4:5], vcc
	s_cbranch_execz .LBB0_1042
	s_waitcnt lgkmcnt(0)
	v_cvt_pk_bf16_f32 v2, v2, v3
	global_store_dword v[0:1], v2, off offset:192
.LBB0_1042:
	s_or_b64 exec, exec, s[4:5]
	v_rcp_f32_e32 v2, v71
	v_lshlrev_b64 v[0:1], 12, v[180:181]
	v_lshl_add_u64 v[0:1], v[80:81], 0, v[0:1]
	s_mov_b64 s[0:1], 0x13000
	s_waitcnt lgkmcnt(0)
	v_mul_f32_e32 v3, v59, v2
	s_nop 1
	v_mov_b32_dpp v4, v3 quad_perm:[1,0,3,2] row_mask:0xf bank_mask:0xf
	v_lshl_add_u64 v[0:1], v[0:1], 0, s[0:1]
	s_and_saveexec_b64 s[4:5], vcc
	s_cbranch_execz .LBB0_1044
	s_waitcnt lgkmcnt(0)
	v_cvt_pk_bf16_f32 v3, v3, v4
	global_store_dword v[0:1], v3, off
.LBB0_1044:
	s_or_b64 exec, exec, s[4:5]
	v_mul_f32_e32 v3, v43, v2
	s_waitcnt lgkmcnt(0)
	s_nop 1
	v_mov_b32_dpp v4, v3 quad_perm:[1,0,3,2] row_mask:0xf bank_mask:0xf
	s_and_saveexec_b64 s[4:5], vcc
	s_cbranch_execz .LBB0_1046
	s_waitcnt lgkmcnt(0)
	v_cvt_pk_bf16_f32 v3, v3, v4
	global_store_dword v[0:1], v3, off offset:64
.LBB0_1046:
	s_or_b64 exec, exec, s[4:5]
	v_mul_f32_e32 v3, v27, v2
	s_waitcnt lgkmcnt(0)
	s_nop 1
	v_mov_b32_dpp v4, v3 quad_perm:[1,0,3,2] row_mask:0xf bank_mask:0xf
	s_and_saveexec_b64 s[4:5], vcc
	s_cbranch_execz .LBB0_1048
	s_waitcnt lgkmcnt(0)
	v_cvt_pk_bf16_f32 v3, v3, v4
	global_store_dword v[0:1], v3, off offset:128
.LBB0_1048:
	s_or_b64 exec, exec, s[4:5]
	v_mul_f32_e32 v2, v11, v2
	s_nop 1
	v_mov_b32_dpp v3, v2 quad_perm:[1,0,3,2] row_mask:0xf bank_mask:0xf
	s_and_saveexec_b64 s[4:5], vcc
	s_cbranch_execz .LBB0_1050
	s_waitcnt lgkmcnt(0)
	v_cvt_pk_bf16_f32 v2, v2, v3
	global_store_dword v[0:1], v2, off offset:192
.LBB0_1050:
	s_or_b64 exec, exec, s[4:5]
	v_rcp_f32_e32 v2, v64
	v_lshlrev_b64 v[0:1], 12, v[180:181]
	v_lshl_add_u64 v[0:1], v[80:81], 0, v[0:1]
	s_mov_b64 s[0:1], 0x18000
	s_waitcnt lgkmcnt(0)
	v_mul_f32_e32 v3, v60, v2
	s_nop 1
	v_mov_b32_dpp v4, v3 quad_perm:[1,0,3,2] row_mask:0xf bank_mask:0xf
	v_lshl_add_u64 v[0:1], v[0:1], 0, s[0:1]
	s_and_saveexec_b64 s[4:5], vcc
	s_cbranch_execz .LBB0_1052
	s_waitcnt lgkmcnt(0)
	v_cvt_pk_bf16_f32 v3, v3, v4
	global_store_dword v[0:1], v3, off
.LBB0_1052:
	s_or_b64 exec, exec, s[4:5]
	v_mul_f32_e32 v3, v44, v2
	s_waitcnt lgkmcnt(0)
	s_nop 1
	v_mov_b32_dpp v4, v3 quad_perm:[1,0,3,2] row_mask:0xf bank_mask:0xf
	s_and_saveexec_b64 s[4:5], vcc
	s_cbranch_execz .LBB0_1054
	s_waitcnt lgkmcnt(0)
	v_cvt_pk_bf16_f32 v3, v3, v4
	global_store_dword v[0:1], v3, off offset:64
.LBB0_1054:
	s_or_b64 exec, exec, s[4:5]
	v_mul_f32_e32 v3, v28, v2
	s_waitcnt lgkmcnt(0)
	s_nop 1
	v_mov_b32_dpp v4, v3 quad_perm:[1,0,3,2] row_mask:0xf bank_mask:0xf
	s_and_saveexec_b64 s[4:5], vcc
	s_cbranch_execz .LBB0_1056
	s_waitcnt lgkmcnt(0)
	v_cvt_pk_bf16_f32 v3, v3, v4
	global_store_dword v[0:1], v3, off offset:128
.LBB0_1056:
	s_or_b64 exec, exec, s[4:5]
	v_mul_f32_e32 v2, v12, v2
	s_nop 1
	v_mov_b32_dpp v3, v2 quad_perm:[1,0,3,2] row_mask:0xf bank_mask:0xf
	s_and_saveexec_b64 s[4:5], vcc
	s_cbranch_execz .LBB0_1058
	s_waitcnt lgkmcnt(0)
	v_cvt_pk_bf16_f32 v2, v2, v3
	global_store_dword v[0:1], v2, off offset:192
.LBB0_1058:
	s_or_b64 exec, exec, s[4:5]
	v_rcp_f32_e32 v2, v65
	v_lshlrev_b64 v[0:1], 12, v[180:181]
	v_lshl_add_u64 v[0:1], v[80:81], 0, v[0:1]
	s_mov_b64 s[0:1], 0x19000
	s_waitcnt lgkmcnt(0)
	v_mul_f32_e32 v3, v61, v2
	s_nop 1
	v_mov_b32_dpp v4, v3 quad_perm:[1,0,3,2] row_mask:0xf bank_mask:0xf
	v_lshl_add_u64 v[0:1], v[0:1], 0, s[0:1]
	s_and_saveexec_b64 s[4:5], vcc
	s_cbranch_execz .LBB0_1060
	s_waitcnt lgkmcnt(0)
	v_cvt_pk_bf16_f32 v3, v3, v4
	global_store_dword v[0:1], v3, off
.LBB0_1060:
	s_or_b64 exec, exec, s[4:5]
	v_mul_f32_e32 v3, v45, v2
	s_waitcnt lgkmcnt(0)
	s_nop 1
	v_mov_b32_dpp v4, v3 quad_perm:[1,0,3,2] row_mask:0xf bank_mask:0xf
	s_and_saveexec_b64 s[4:5], vcc
	s_cbranch_execz .LBB0_1062
	s_waitcnt lgkmcnt(0)
	v_cvt_pk_bf16_f32 v3, v3, v4
	global_store_dword v[0:1], v3, off offset:64
.LBB0_1062:
	s_or_b64 exec, exec, s[4:5]
	v_mul_f32_e32 v3, v29, v2
	s_waitcnt lgkmcnt(0)
	s_nop 1
	v_mov_b32_dpp v4, v3 quad_perm:[1,0,3,2] row_mask:0xf bank_mask:0xf
	s_and_saveexec_b64 s[4:5], vcc
	s_cbranch_execz .LBB0_1064
	s_waitcnt lgkmcnt(0)
	v_cvt_pk_bf16_f32 v3, v3, v4
	global_store_dword v[0:1], v3, off offset:128
.LBB0_1064:
	s_or_b64 exec, exec, s[4:5]
	v_mul_f32_e32 v2, v13, v2
	s_nop 1
	v_mov_b32_dpp v3, v2 quad_perm:[1,0,3,2] row_mask:0xf bank_mask:0xf
	s_and_saveexec_b64 s[4:5], vcc
	s_cbranch_execz .LBB0_1066
	s_waitcnt lgkmcnt(0)
	v_cvt_pk_bf16_f32 v2, v2, v3
	global_store_dword v[0:1], v2, off offset:192
.LBB0_1066:
	s_or_b64 exec, exec, s[4:5]
	v_rcp_f32_e32 v2, v66
	v_lshlrev_b64 v[0:1], 12, v[180:181]
	v_lshl_add_u64 v[0:1], v[80:81], 0, v[0:1]
	v_lshl_add_u64 v[0:1], v[0:1], 0, s[66:67]
	s_waitcnt lgkmcnt(0)
	v_mul_f32_e32 v3, v62, v2
	s_nop 1
	v_mov_b32_dpp v4, v3 quad_perm:[1,0,3,2] row_mask:0xf bank_mask:0xf
	s_and_saveexec_b64 s[4:5], vcc
	s_cbranch_execz .LBB0_1068
	s_waitcnt lgkmcnt(0)
	v_cvt_pk_bf16_f32 v3, v3, v4
	global_store_dword v[0:1], v3, off
.LBB0_1068:
	s_or_b64 exec, exec, s[4:5]
	v_mul_f32_e32 v3, v46, v2
	s_waitcnt lgkmcnt(0)
	s_nop 1
	v_mov_b32_dpp v4, v3 quad_perm:[1,0,3,2] row_mask:0xf bank_mask:0xf
	s_and_saveexec_b64 s[4:5], vcc
	s_cbranch_execz .LBB0_1070
	s_waitcnt lgkmcnt(0)
	v_cvt_pk_bf16_f32 v3, v3, v4
	global_store_dword v[0:1], v3, off offset:64
.LBB0_1070:
	s_or_b64 exec, exec, s[4:5]
	v_mul_f32_e32 v3, v30, v2
	s_waitcnt lgkmcnt(0)
	s_nop 1
	v_mov_b32_dpp v4, v3 quad_perm:[1,0,3,2] row_mask:0xf bank_mask:0xf
	s_and_saveexec_b64 s[4:5], vcc
	s_cbranch_execz .LBB0_1072
	s_waitcnt lgkmcnt(0)
	v_cvt_pk_bf16_f32 v3, v3, v4
	global_store_dword v[0:1], v3, off offset:128
.LBB0_1072:
	s_or_b64 exec, exec, s[4:5]
	v_mul_f32_e32 v2, v14, v2
	s_nop 1
	v_mov_b32_dpp v3, v2 quad_perm:[1,0,3,2] row_mask:0xf bank_mask:0xf
	s_and_saveexec_b64 s[4:5], vcc
	s_cbranch_execz .LBB0_1074
	s_waitcnt lgkmcnt(0)
	v_cvt_pk_bf16_f32 v2, v2, v3
	global_store_dword v[0:1], v2, off offset:192
.LBB0_1074:
	s_or_b64 exec, exec, s[4:5]
	v_rcp_f32_e32 v2, v67
	v_lshlrev_b64 v[0:1], 12, v[180:181]
	v_lshl_add_u64 v[0:1], v[80:81], 0, v[0:1]
	v_lshl_add_u64 v[0:1], v[0:1], 0, s[68:69]
	s_waitcnt lgkmcnt(0)
	v_mul_f32_e32 v3, v63, v2
	s_nop 1
	v_mov_b32_dpp v4, v3 quad_perm:[1,0,3,2] row_mask:0xf bank_mask:0xf
	s_and_saveexec_b64 s[4:5], vcc
	s_cbranch_execz .LBB0_1076
	s_waitcnt lgkmcnt(0)
	v_cvt_pk_bf16_f32 v3, v3, v4
	global_store_dword v[0:1], v3, off
.LBB0_1076:
	s_or_b64 exec, exec, s[4:5]
	v_mul_f32_e32 v3, v47, v2
	s_waitcnt lgkmcnt(0)
	s_nop 1
	v_mov_b32_dpp v4, v3 quad_perm:[1,0,3,2] row_mask:0xf bank_mask:0xf
	s_and_saveexec_b64 s[4:5], vcc
	s_cbranch_execz .LBB0_1078
	s_waitcnt lgkmcnt(0)
	v_cvt_pk_bf16_f32 v3, v3, v4
	global_store_dword v[0:1], v3, off offset:64
.LBB0_1078:
	s_or_b64 exec, exec, s[4:5]
	v_mul_f32_e32 v3, v31, v2
	s_waitcnt lgkmcnt(0)
	s_nop 1
	v_mov_b32_dpp v4, v3 quad_perm:[1,0,3,2] row_mask:0xf bank_mask:0xf
	s_and_saveexec_b64 s[4:5], vcc
	s_cbranch_execz .LBB0_1080
	s_waitcnt lgkmcnt(0)
	v_cvt_pk_bf16_f32 v3, v3, v4
	global_store_dword v[0:1], v3, off offset:128
.LBB0_1080:
	s_or_b64 exec, exec, s[4:5]
	v_mul_f32_e32 v2, v15, v2
	s_nop 1
	v_mov_b32_dpp v3, v2 quad_perm:[1,0,3,2] row_mask:0xf bank_mask:0xf
	s_and_saveexec_b64 s[4:5], vcc
	s_cbranch_execz .LBB0_853
	s_waitcnt lgkmcnt(0)
	v_cvt_pk_bf16_f32 v2, v2, v3
	global_store_dword v[0:1], v2, off offset:192
	s_branch .LBB0_853

.LBB0_1135:
	s_or_b64 exec, exec, s[4:5]
	s_waitcnt lgkmcnt(0)
	ds_read_b128 v[76:79], v183
	ds_read_b128 v[72:75], v183 offset:32
	s_or_b64 s[4:5], s[50:51], s[70:71]
	s_lshl_b64 s[4:5], s[4:5], 12
	s_add_u32 s0, s19, s4
	s_waitcnt lgkmcnt(1)
	v_rcp_f32_e32 v76, v76
	s_addc_u32 s3, s28, s5
	s_lshl_b32 s1, s1, 8
	s_add_u32 s0, s0, s1
	v_mul_f32_e32 v0, v0, v76
	s_addc_u32 s1, s3, 0
	ds_read_b128 v[68:71], v183 offset:64
	ds_read_b128 v[64:67], v183 offset:96
	s_nop 1
	v_mov_b32_dpp v84, v0 quad_perm:[1,0,3,2] row_mask:0xf bank_mask:0xf
	s_add_u32 s0, s0, s8
	s_addc_u32 s1, s1, s9
	v_and_b32_e32 v80, 1, v165
	v_lshlrev_b32_e32 v130, 1, v171
	v_ashrrev_i32_e32 v165, 31, v164
	v_cmp_eq_u32_e32 vcc, 0, v80
	v_lshl_add_u64 v[80:81], s[0:1], 0, v[130:131]
	v_lshlrev_b64 v[82:83], 12, v[164:165]
	v_lshl_add_u64 v[82:83], v[80:81], 0, v[82:83]
	s_and_saveexec_b64 s[4:5], vcc
	s_cbranch_execz .LBB0_1137
	s_waitcnt lgkmcnt(0)
	v_cvt_pk_bf16_f32 v0, v0, v84
	global_store_dword v[82:83], v0, off offset:3072
.LBB0_1137:
	s_or_b64 exec, exec, s[4:5]
	v_mul_f32_e32 v0, v16, v76
	s_nop 1
	v_mov_b32_dpp v16, v0 quad_perm:[1,0,3,2] row_mask:0xf bank_mask:0xf
	s_and_saveexec_b64 s[4:5], vcc
	s_cbranch_execz .LBB0_1139
	s_waitcnt lgkmcnt(0)
	v_cvt_pk_bf16_f32 v0, v0, v16
	global_store_dword v[82:83], v0, off offset:3136
.LBB0_1139:
	s_or_b64 exec, exec, s[4:5]
	v_mul_f32_e32 v0, v32, v76
	s_waitcnt lgkmcnt(0)
	s_nop 1
	v_mov_b32_dpp v16, v0 quad_perm:[1,0,3,2] row_mask:0xf bank_mask:0xf
	s_and_saveexec_b64 s[4:5], vcc
	s_cbranch_execz .LBB0_1141
	s_waitcnt lgkmcnt(0)
	v_cvt_pk_bf16_f32 v0, v0, v16
	global_store_dword v[82:83], v0, off offset:3200
.LBB0_1141:
	s_or_b64 exec, exec, s[4:5]
	v_mul_f32_e32 v0, v48, v76
	s_waitcnt lgkmcnt(0)
	s_nop 1
	v_mov_b32_dpp v16, v0 quad_perm:[1,0,3,2] row_mask:0xf bank_mask:0xf
	s_and_saveexec_b64 s[4:5], vcc
	s_cbranch_execz .LBB0_1143
	s_waitcnt lgkmcnt(0)
	v_cvt_pk_bf16_f32 v0, v0, v16
	global_store_dword v[82:83], v0, off offset:3264
.LBB0_1143:
	s_or_b64 exec, exec, s[4:5]
	v_rcp_f32_e32 v0, v77
	v_or_b32_e32 v76, 1, v164
	v_ashrrev_i32_e32 v77, 31, v76
	v_lshlrev_b64 v[76:77], 12, v[76:77]
	v_mul_f32_e32 v1, v1, v0
	s_waitcnt lgkmcnt(0)
	s_nop 1
	v_mov_b32_dpp v16, v1 quad_perm:[1,0,3,2] row_mask:0xf bank_mask:0xf
	v_lshl_add_u64 v[76:77], v[80:81], 0, v[76:77]
	s_and_saveexec_b64 s[4:5], vcc
	s_cbranch_execz .LBB0_1145
	s_waitcnt lgkmcnt(0)
	v_cvt_pk_bf16_f32 v1, v1, v16
	global_store_dword v[76:77], v1, off offset:3072
.LBB0_1145:
	s_or_b64 exec, exec, s[4:5]
	v_mul_f32_e32 v1, v17, v0
	s_waitcnt lgkmcnt(0)
	s_nop 1
	v_mov_b32_dpp v16, v1 quad_perm:[1,0,3,2] row_mask:0xf bank_mask:0xf
	s_and_saveexec_b64 s[4:5], vcc
	s_cbranch_execz .LBB0_1147
	s_waitcnt lgkmcnt(0)
	v_cvt_pk_bf16_f32 v1, v1, v16
	global_store_dword v[76:77], v1, off offset:3136
.LBB0_1147:
	s_or_b64 exec, exec, s[4:5]
	v_mul_f32_e32 v1, v33, v0
	s_waitcnt lgkmcnt(0)
	s_nop 1
	v_mov_b32_dpp v16, v1 quad_perm:[1,0,3,2] row_mask:0xf bank_mask:0xf
	s_and_saveexec_b64 s[4:5], vcc
	s_cbranch_execz .LBB0_1149
	s_waitcnt lgkmcnt(0)
	v_cvt_pk_bf16_f32 v1, v1, v16
	global_store_dword v[76:77], v1, off offset:3200
.LBB0_1149:
	s_or_b64 exec, exec, s[4:5]
	v_mul_f32_e32 v0, v49, v0
	s_nop 1
	v_mov_b32_dpp v1, v0 quad_perm:[1,0,3,2] row_mask:0xf bank_mask:0xf
	s_and_saveexec_b64 s[4:5], vcc
	s_cbranch_execz .LBB0_1151
	s_waitcnt lgkmcnt(0)
	v_cvt_pk_bf16_f32 v0, v0, v1
	global_store_dword v[76:77], v0, off offset:3264
.LBB0_1151:
	s_or_b64 exec, exec, s[4:5]
	s_waitcnt lgkmcnt(0)
	v_rcp_f32_e32 v16, v78
	v_or_b32_e32 v0, 2, v164
	v_ashrrev_i32_e32 v1, 31, v0
	v_lshlrev_b64 v[0:1], 12, v[0:1]
	v_mul_f32_e32 v2, v2, v16
	s_nop 1
	v_mov_b32_dpp v17, v2 quad_perm:[1,0,3,2] row_mask:0xf bank_mask:0xf
	v_lshl_add_u64 v[0:1], v[80:81], 0, v[0:1]
	s_and_saveexec_b64 s[4:5], vcc
	s_cbranch_execz .LBB0_1153
	s_waitcnt lgkmcnt(0)
	v_cvt_pk_bf16_f32 v2, v2, v17
	global_store_dword v[0:1], v2, off offset:3072
.LBB0_1153:
	s_or_b64 exec, exec, s[4:5]
	v_mul_f32_e32 v2, v18, v16
	s_waitcnt lgkmcnt(0)
	s_nop 1
	v_mov_b32_dpp v17, v2 quad_perm:[1,0,3,2] row_mask:0xf bank_mask:0xf
	s_and_saveexec_b64 s[4:5], vcc
	s_cbranch_execz .LBB0_1155
	s_waitcnt lgkmcnt(0)
	v_cvt_pk_bf16_f32 v2, v2, v17
	global_store_dword v[0:1], v2, off offset:3136
.LBB0_1155:
	s_or_b64 exec, exec, s[4:5]
	v_mul_f32_e32 v2, v34, v16
	s_waitcnt lgkmcnt(0)
	s_nop 1
	v_mov_b32_dpp v17, v2 quad_perm:[1,0,3,2] row_mask:0xf bank_mask:0xf
	s_and_saveexec_b64 s[4:5], vcc
	s_cbranch_execz .LBB0_1157
	s_waitcnt lgkmcnt(0)
	v_cvt_pk_bf16_f32 v2, v2, v17
	global_store_dword v[0:1], v2, off offset:3200
.LBB0_1157:
	s_or_b64 exec, exec, s[4:5]
	v_mul_f32_e32 v2, v50, v16
	s_nop 1
	v_mov_b32_dpp v16, v2 quad_perm:[1,0,3,2] row_mask:0xf bank_mask:0xf
	s_and_saveexec_b64 s[4:5], vcc
	s_cbranch_execz .LBB0_1159
	s_waitcnt lgkmcnt(0)
	v_cvt_pk_bf16_f32 v2, v2, v16
	global_store_dword v[0:1], v2, off offset:3264
.LBB0_1159:
	s_or_b64 exec, exec, s[4:5]
	v_rcp_f32_e32 v2, v79
	v_or_b32_e32 v0, 3, v164
	v_ashrrev_i32_e32 v1, 31, v0
	v_lshlrev_b64 v[0:1], 12, v[0:1]
	v_mul_f32_e32 v3, v3, v2
	s_waitcnt lgkmcnt(0)
	s_nop 1
	v_mov_b32_dpp v16, v3 quad_perm:[1,0,3,2] row_mask:0xf bank_mask:0xf
	v_lshl_add_u64 v[0:1], v[80:81], 0, v[0:1]
	s_and_saveexec_b64 s[4:5], vcc
	s_cbranch_execz .LBB0_1161
	s_waitcnt lgkmcnt(0)
	v_cvt_pk_bf16_f32 v3, v3, v16
	global_store_dword v[0:1], v3, off offset:3072
.LBB0_1161:
	s_or_b64 exec, exec, s[4:5]
	v_mul_f32_e32 v3, v19, v2
	s_waitcnt lgkmcnt(0)
	s_nop 1
	v_mov_b32_dpp v16, v3 quad_perm:[1,0,3,2] row_mask:0xf bank_mask:0xf
	s_and_saveexec_b64 s[4:5], vcc
	s_cbranch_execz .LBB0_1163
	s_waitcnt lgkmcnt(0)
	v_cvt_pk_bf16_f32 v3, v3, v16
	global_store_dword v[0:1], v3, off offset:3136
.LBB0_1163:
	s_or_b64 exec, exec, s[4:5]
	v_mul_f32_e32 v3, v35, v2
	s_waitcnt lgkmcnt(0)
	s_nop 1
	v_mov_b32_dpp v16, v3 quad_perm:[1,0,3,2] row_mask:0xf bank_mask:0xf
	s_and_saveexec_b64 s[4:5], vcc
	s_cbranch_execz .LBB0_1165
	s_waitcnt lgkmcnt(0)
	v_cvt_pk_bf16_f32 v3, v3, v16
	global_store_dword v[0:1], v3, off offset:3200
.LBB0_1165:
	s_or_b64 exec, exec, s[4:5]
	v_mul_f32_e32 v2, v51, v2
	s_nop 1
	v_mov_b32_dpp v3, v2 quad_perm:[1,0,3,2] row_mask:0xf bank_mask:0xf
	s_and_saveexec_b64 s[4:5], vcc
	s_cbranch_execz .LBB0_1167
	s_waitcnt lgkmcnt(0)
	v_cvt_pk_bf16_f32 v2, v2, v3
	global_store_dword v[0:1], v2, off offset:3264
.LBB0_1167:
	s_or_b64 exec, exec, s[4:5]
	v_rcp_f32_e32 v2, v72
	v_lshlrev_b64 v[0:1], 12, v[164:165]
	v_lshl_add_u64 v[0:1], v[80:81], 0, v[0:1]
	v_lshl_add_u64 v[0:1], v[0:1], 0, s[34:35]
	s_waitcnt lgkmcnt(0)
	v_mul_f32_e32 v3, v4, v2
	s_nop 1
	v_mov_b32_dpp v4, v3 quad_perm:[1,0,3,2] row_mask:0xf bank_mask:0xf
	s_and_saveexec_b64 s[4:5], vcc
	s_cbranch_execz .LBB0_1169
	s_waitcnt lgkmcnt(0)
	v_cvt_pk_bf16_f32 v3, v3, v4
	global_store_dword v[0:1], v3, off offset:3072
.LBB0_1169:
	s_or_b64 exec, exec, s[4:5]
	v_mul_f32_e32 v3, v20, v2
	s_waitcnt lgkmcnt(0)
	s_nop 1
	v_mov_b32_dpp v4, v3 quad_perm:[1,0,3,2] row_mask:0xf bank_mask:0xf
	s_and_saveexec_b64 s[4:5], vcc
	s_cbranch_execz .LBB0_1171
	s_waitcnt lgkmcnt(0)
	v_cvt_pk_bf16_f32 v3, v3, v4
	global_store_dword v[0:1], v3, off offset:3136
.LBB0_1171:
	s_or_b64 exec, exec, s[4:5]
	v_mul_f32_e32 v3, v36, v2
	s_waitcnt lgkmcnt(0)
	s_nop 1
	v_mov_b32_dpp v4, v3 quad_perm:[1,0,3,2] row_mask:0xf bank_mask:0xf
	s_and_saveexec_b64 s[4:5], vcc
	s_cbranch_execz .LBB0_1173
	s_waitcnt lgkmcnt(0)
	v_cvt_pk_bf16_f32 v3, v3, v4
	global_store_dword v[0:1], v3, off offset:3200
.LBB0_1173:
	s_or_b64 exec, exec, s[4:5]
	v_mul_f32_e32 v2, v52, v2
	s_nop 1
	v_mov_b32_dpp v3, v2 quad_perm:[1,0,3,2] row_mask:0xf bank_mask:0xf
	s_and_saveexec_b64 s[4:5], vcc
	s_cbranch_execz .LBB0_1175
	s_waitcnt lgkmcnt(0)
	v_cvt_pk_bf16_f32 v2, v2, v3
	global_store_dword v[0:1], v2, off offset:3264
.LBB0_1175:
	s_or_b64 exec, exec, s[4:5]
	v_rcp_f32_e32 v2, v73
	v_lshlrev_b64 v[0:1], 12, v[164:165]
	v_lshl_add_u64 v[0:1], v[80:81], 0, v[0:1]
	v_lshl_add_u64 v[0:1], v[0:1], 0, s[48:49]
	s_waitcnt lgkmcnt(0)
	v_mul_f32_e32 v3, v5, v2
	s_nop 1
	v_mov_b32_dpp v4, v3 quad_perm:[1,0,3,2] row_mask:0xf bank_mask:0xf
	s_and_saveexec_b64 s[4:5], vcc
	s_cbranch_execz .LBB0_1177
	s_waitcnt lgkmcnt(0)
	v_cvt_pk_bf16_f32 v3, v3, v4
	global_store_dword v[0:1], v3, off offset:3072
.LBB0_1177:
	s_or_b64 exec, exec, s[4:5]
	v_mul_f32_e32 v3, v21, v2
	s_waitcnt lgkmcnt(0)
	s_nop 1
	v_mov_b32_dpp v4, v3 quad_perm:[1,0,3,2] row_mask:0xf bank_mask:0xf
	s_and_saveexec_b64 s[4:5], vcc
	s_cbranch_execz .LBB0_1179
	s_waitcnt lgkmcnt(0)
	v_cvt_pk_bf16_f32 v3, v3, v4
	global_store_dword v[0:1], v3, off offset:3136
.LBB0_1179:
	s_or_b64 exec, exec, s[4:5]
	v_mul_f32_e32 v3, v37, v2
	s_waitcnt lgkmcnt(0)
	s_nop 1
	v_mov_b32_dpp v4, v3 quad_perm:[1,0,3,2] row_mask:0xf bank_mask:0xf
	s_and_saveexec_b64 s[4:5], vcc
	s_cbranch_execz .LBB0_1181
	s_waitcnt lgkmcnt(0)
	v_cvt_pk_bf16_f32 v3, v3, v4
	global_store_dword v[0:1], v3, off offset:3200
.LBB0_1181:
	s_or_b64 exec, exec, s[4:5]
	v_mul_f32_e32 v2, v53, v2
	s_nop 1
	v_mov_b32_dpp v3, v2 quad_perm:[1,0,3,2] row_mask:0xf bank_mask:0xf
	s_and_saveexec_b64 s[4:5], vcc
	s_cbranch_execz .LBB0_1183
	s_waitcnt lgkmcnt(0)
	v_cvt_pk_bf16_f32 v2, v2, v3
	global_store_dword v[0:1], v2, off offset:3264
.LBB0_1183:
	s_or_b64 exec, exec, s[4:5]
	v_rcp_f32_e32 v2, v74
	v_lshlrev_b64 v[0:1], 12, v[164:165]
	v_lshl_add_u64 v[0:1], v[80:81], 0, v[0:1]
	v_lshl_add_u64 v[0:1], v[0:1], 0, s[54:55]
	s_waitcnt lgkmcnt(0)
	v_mul_f32_e32 v3, v6, v2
	s_nop 1
	v_mov_b32_dpp v4, v3 quad_perm:[1,0,3,2] row_mask:0xf bank_mask:0xf
	s_and_saveexec_b64 s[4:5], vcc
	s_cbranch_execz .LBB0_1185
	s_waitcnt lgkmcnt(0)
	v_cvt_pk_bf16_f32 v3, v3, v4
	global_store_dword v[0:1], v3, off offset:3072
.LBB0_1185:
	s_or_b64 exec, exec, s[4:5]
	v_mul_f32_e32 v3, v22, v2
	s_waitcnt lgkmcnt(0)
	s_nop 1
	v_mov_b32_dpp v4, v3 quad_perm:[1,0,3,2] row_mask:0xf bank_mask:0xf
	s_and_saveexec_b64 s[4:5], vcc
	s_cbranch_execz .LBB0_1187
	s_waitcnt lgkmcnt(0)
	v_cvt_pk_bf16_f32 v3, v3, v4
	global_store_dword v[0:1], v3, off offset:3136
.LBB0_1187:
	s_or_b64 exec, exec, s[4:5]
	v_mul_f32_e32 v3, v38, v2
	s_waitcnt lgkmcnt(0)
	s_nop 1
	v_mov_b32_dpp v4, v3 quad_perm:[1,0,3,2] row_mask:0xf bank_mask:0xf
	s_and_saveexec_b64 s[4:5], vcc
	s_cbranch_execz .LBB0_1189
	s_waitcnt lgkmcnt(0)
	v_cvt_pk_bf16_f32 v3, v3, v4
	global_store_dword v[0:1], v3, off offset:3200
.LBB0_1189:
	s_or_b64 exec, exec, s[4:5]
	v_mul_f32_e32 v2, v54, v2
	s_nop 1
	v_mov_b32_dpp v3, v2 quad_perm:[1,0,3,2] row_mask:0xf bank_mask:0xf
	s_and_saveexec_b64 s[4:5], vcc
	s_cbranch_execz .LBB0_1191
	s_waitcnt lgkmcnt(0)
	v_cvt_pk_bf16_f32 v2, v2, v3
	global_store_dword v[0:1], v2, off offset:3264
.LBB0_1191:
	s_or_b64 exec, exec, s[4:5]
	v_rcp_f32_e32 v2, v75
	v_lshlrev_b64 v[0:1], 12, v[164:165]
	v_lshl_add_u64 v[0:1], v[80:81], 0, v[0:1]
	v_lshl_add_u64 v[0:1], v[0:1], 0, s[40:41]
	s_waitcnt lgkmcnt(0)
	v_mul_f32_e32 v3, v7, v2
	s_nop 1
	v_mov_b32_dpp v4, v3 quad_perm:[1,0,3,2] row_mask:0xf bank_mask:0xf
	s_and_saveexec_b64 s[4:5], vcc
	s_cbranch_execz .LBB0_1193
	s_waitcnt lgkmcnt(0)
	v_cvt_pk_bf16_f32 v3, v3, v4
	global_store_dword v[0:1], v3, off offset:3072
.LBB0_1193:
	s_or_b64 exec, exec, s[4:5]
	v_mul_f32_e32 v3, v23, v2
	s_waitcnt lgkmcnt(0)
	s_nop 1
	v_mov_b32_dpp v4, v3 quad_perm:[1,0,3,2] row_mask:0xf bank_mask:0xf
	s_and_saveexec_b64 s[4:5], vcc
	s_cbranch_execz .LBB0_1195
	s_waitcnt lgkmcnt(0)
	v_cvt_pk_bf16_f32 v3, v3, v4
	global_store_dword v[0:1], v3, off offset:3136
.LBB0_1195:
	s_or_b64 exec, exec, s[4:5]
	v_mul_f32_e32 v3, v39, v2
	s_waitcnt lgkmcnt(0)
	s_nop 1
	v_mov_b32_dpp v4, v3 quad_perm:[1,0,3,2] row_mask:0xf bank_mask:0xf
	s_and_saveexec_b64 s[4:5], vcc
	s_cbranch_execz .LBB0_1197
	s_waitcnt lgkmcnt(0)
	v_cvt_pk_bf16_f32 v3, v3, v4
	global_store_dword v[0:1], v3, off offset:3200
.LBB0_1197:
	s_or_b64 exec, exec, s[4:5]
	v_mul_f32_e32 v2, v55, v2
	s_nop 1
	v_mov_b32_dpp v3, v2 quad_perm:[1,0,3,2] row_mask:0xf bank_mask:0xf
	s_and_saveexec_b64 s[4:5], vcc
	s_cbranch_execz .LBB0_1199
	s_waitcnt lgkmcnt(0)
	v_cvt_pk_bf16_f32 v2, v2, v3
	global_store_dword v[0:1], v2, off offset:3264
.LBB0_1199:
	s_or_b64 exec, exec, s[4:5]
	v_rcp_f32_e32 v2, v68
	v_lshlrev_b64 v[0:1], 12, v[164:165]
	v_lshl_add_u64 v[0:1], v[80:81], 0, v[0:1]
	s_mov_b64 s[0:1], 0x10000
	s_waitcnt lgkmcnt(0)
	v_mul_f32_e32 v3, v8, v2
	s_nop 1
	v_mov_b32_dpp v4, v3 quad_perm:[1,0,3,2] row_mask:0xf bank_mask:0xf
	v_lshl_add_u64 v[0:1], v[0:1], 0, s[0:1]
	s_and_saveexec_b64 s[4:5], vcc
	s_cbranch_execz .LBB0_1201
	s_waitcnt lgkmcnt(0)
	v_cvt_pk_bf16_f32 v3, v3, v4
	global_store_dword v[0:1], v3, off offset:3072
.LBB0_1201:
	s_or_b64 exec, exec, s[4:5]
	v_mul_f32_e32 v3, v24, v2
	s_waitcnt lgkmcnt(0)
	s_nop 1
	v_mov_b32_dpp v4, v3 quad_perm:[1,0,3,2] row_mask:0xf bank_mask:0xf
	s_and_saveexec_b64 s[4:5], vcc
	s_cbranch_execz .LBB0_1203
	s_waitcnt lgkmcnt(0)
	v_cvt_pk_bf16_f32 v3, v3, v4
	global_store_dword v[0:1], v3, off offset:3136
.LBB0_1203:
	s_or_b64 exec, exec, s[4:5]
	v_mul_f32_e32 v3, v40, v2
	s_waitcnt lgkmcnt(0)
	s_nop 1
	v_mov_b32_dpp v4, v3 quad_perm:[1,0,3,2] row_mask:0xf bank_mask:0xf
	s_and_saveexec_b64 s[4:5], vcc
	s_cbranch_execz .LBB0_1205
	s_waitcnt lgkmcnt(0)
	v_cvt_pk_bf16_f32 v3, v3, v4
	global_store_dword v[0:1], v3, off offset:3200
.LBB0_1205:
	s_or_b64 exec, exec, s[4:5]
	v_mul_f32_e32 v2, v56, v2
	s_nop 1
	v_mov_b32_dpp v3, v2 quad_perm:[1,0,3,2] row_mask:0xf bank_mask:0xf
	s_and_saveexec_b64 s[4:5], vcc
	s_cbranch_execz .LBB0_1207
	s_waitcnt lgkmcnt(0)
	v_cvt_pk_bf16_f32 v2, v2, v3
	global_store_dword v[0:1], v2, off offset:3264
.LBB0_1207:
	s_or_b64 exec, exec, s[4:5]
	v_rcp_f32_e32 v2, v69
	v_lshlrev_b64 v[0:1], 12, v[164:165]
	v_lshl_add_u64 v[0:1], v[80:81], 0, v[0:1]
	s_mov_b64 s[0:1], 0x11000
	s_waitcnt lgkmcnt(0)
	v_mul_f32_e32 v3, v9, v2
	s_nop 1
	v_mov_b32_dpp v4, v3 quad_perm:[1,0,3,2] row_mask:0xf bank_mask:0xf
	v_lshl_add_u64 v[0:1], v[0:1], 0, s[0:1]
	s_and_saveexec_b64 s[4:5], vcc
	s_cbranch_execz .LBB0_1209
	s_waitcnt lgkmcnt(0)
	v_cvt_pk_bf16_f32 v3, v3, v4
	global_store_dword v[0:1], v3, off offset:3072
.LBB0_1209:
	s_or_b64 exec, exec, s[4:5]
	v_mul_f32_e32 v3, v25, v2
	s_waitcnt lgkmcnt(0)
	s_nop 1
	v_mov_b32_dpp v4, v3 quad_perm:[1,0,3,2] row_mask:0xf bank_mask:0xf
	s_and_saveexec_b64 s[4:5], vcc
	s_cbranch_execz .LBB0_1211
	s_waitcnt lgkmcnt(0)
	v_cvt_pk_bf16_f32 v3, v3, v4
	global_store_dword v[0:1], v3, off offset:3136
.LBB0_1211:
	s_or_b64 exec, exec, s[4:5]
	v_mul_f32_e32 v3, v41, v2
	s_waitcnt lgkmcnt(0)
	s_nop 1
	v_mov_b32_dpp v4, v3 quad_perm:[1,0,3,2] row_mask:0xf bank_mask:0xf
	s_and_saveexec_b64 s[4:5], vcc
	s_cbranch_execz .LBB0_1213
	s_waitcnt lgkmcnt(0)
	v_cvt_pk_bf16_f32 v3, v3, v4
	global_store_dword v[0:1], v3, off offset:3200
.LBB0_1213:
	s_or_b64 exec, exec, s[4:5]
	v_mul_f32_e32 v2, v57, v2
	s_nop 1
	v_mov_b32_dpp v3, v2 quad_perm:[1,0,3,2] row_mask:0xf bank_mask:0xf
	s_and_saveexec_b64 s[4:5], vcc
	s_cbranch_execz .LBB0_1215
	s_waitcnt lgkmcnt(0)
	v_cvt_pk_bf16_f32 v2, v2, v3
	global_store_dword v[0:1], v2, off offset:3264
.LBB0_1215:
	s_or_b64 exec, exec, s[4:5]
	v_rcp_f32_e32 v2, v70
	v_lshlrev_b64 v[0:1], 12, v[164:165]
	v_lshl_add_u64 v[0:1], v[80:81], 0, v[0:1]
	v_lshl_add_u64 v[0:1], v[0:1], 0, s[56:57]
	s_waitcnt lgkmcnt(0)
	v_mul_f32_e32 v3, v10, v2
	s_nop 1
	v_mov_b32_dpp v4, v3 quad_perm:[1,0,3,2] row_mask:0xf bank_mask:0xf
	s_and_saveexec_b64 s[4:5], vcc
	s_cbranch_execz .LBB0_1217
	s_waitcnt lgkmcnt(0)
	v_cvt_pk_bf16_f32 v3, v3, v4
	global_store_dword v[0:1], v3, off offset:3072
.LBB0_1217:
	s_or_b64 exec, exec, s[4:5]
	v_mul_f32_e32 v3, v26, v2
	s_waitcnt lgkmcnt(0)
	s_nop 1
	v_mov_b32_dpp v4, v3 quad_perm:[1,0,3,2] row_mask:0xf bank_mask:0xf
	s_and_saveexec_b64 s[4:5], vcc
	s_cbranch_execz .LBB0_1219
	s_waitcnt lgkmcnt(0)
	v_cvt_pk_bf16_f32 v3, v3, v4
	global_store_dword v[0:1], v3, off offset:3136
.LBB0_1219:
	s_or_b64 exec, exec, s[4:5]
	v_mul_f32_e32 v3, v42, v2
	s_waitcnt lgkmcnt(0)
	s_nop 1
	v_mov_b32_dpp v4, v3 quad_perm:[1,0,3,2] row_mask:0xf bank_mask:0xf
	s_and_saveexec_b64 s[4:5], vcc
	s_cbranch_execz .LBB0_1221
	s_waitcnt lgkmcnt(0)
	v_cvt_pk_bf16_f32 v3, v3, v4
	global_store_dword v[0:1], v3, off offset:3200
.LBB0_1221:
	s_or_b64 exec, exec, s[4:5]
	v_mul_f32_e32 v2, v58, v2
	s_nop 1
	v_mov_b32_dpp v3, v2 quad_perm:[1,0,3,2] row_mask:0xf bank_mask:0xf
	s_and_saveexec_b64 s[4:5], vcc
	s_cbranch_execz .LBB0_1223
	s_waitcnt lgkmcnt(0)
	v_cvt_pk_bf16_f32 v2, v2, v3
	global_store_dword v[0:1], v2, off offset:3264
.LBB0_1223:
	s_or_b64 exec, exec, s[4:5]
	v_rcp_f32_e32 v2, v71
	v_lshlrev_b64 v[0:1], 12, v[164:165]
	v_lshl_add_u64 v[0:1], v[80:81], 0, v[0:1]
	s_mov_b64 s[0:1], 0x13000
	s_waitcnt lgkmcnt(0)
	v_mul_f32_e32 v3, v11, v2
	s_nop 1
	v_mov_b32_dpp v4, v3 quad_perm:[1,0,3,2] row_mask:0xf bank_mask:0xf
	v_lshl_add_u64 v[0:1], v[0:1], 0, s[0:1]
	s_and_saveexec_b64 s[4:5], vcc
	s_cbranch_execz .LBB0_1225
	s_waitcnt lgkmcnt(0)
	v_cvt_pk_bf16_f32 v3, v3, v4
	global_store_dword v[0:1], v3, off offset:3072
.LBB0_1225:
	s_or_b64 exec, exec, s[4:5]
	v_mul_f32_e32 v3, v27, v2
	s_waitcnt lgkmcnt(0)
	s_nop 1
	v_mov_b32_dpp v4, v3 quad_perm:[1,0,3,2] row_mask:0xf bank_mask:0xf
	s_and_saveexec_b64 s[4:5], vcc
	s_cbranch_execz .LBB0_1227
	s_waitcnt lgkmcnt(0)
	v_cvt_pk_bf16_f32 v3, v3, v4
	global_store_dword v[0:1], v3, off offset:3136
.LBB0_1227:
	s_or_b64 exec, exec, s[4:5]
	v_mul_f32_e32 v3, v43, v2
	s_waitcnt lgkmcnt(0)
	s_nop 1
	v_mov_b32_dpp v4, v3 quad_perm:[1,0,3,2] row_mask:0xf bank_mask:0xf
	s_and_saveexec_b64 s[4:5], vcc
	s_cbranch_execz .LBB0_1229
	s_waitcnt lgkmcnt(0)
	v_cvt_pk_bf16_f32 v3, v3, v4
	global_store_dword v[0:1], v3, off offset:3200
.LBB0_1229:
	s_or_b64 exec, exec, s[4:5]
	v_mul_f32_e32 v2, v59, v2
	s_nop 1
	v_mov_b32_dpp v3, v2 quad_perm:[1,0,3,2] row_mask:0xf bank_mask:0xf
	s_and_saveexec_b64 s[4:5], vcc
	s_cbranch_execz .LBB0_1231
	s_waitcnt lgkmcnt(0)
	v_cvt_pk_bf16_f32 v2, v2, v3
	global_store_dword v[0:1], v2, off offset:3264
.LBB0_1231:
	s_or_b64 exec, exec, s[4:5]
	v_rcp_f32_e32 v2, v64
	v_lshlrev_b64 v[0:1], 12, v[164:165]
	v_lshl_add_u64 v[0:1], v[80:81], 0, v[0:1]
	s_mov_b64 s[0:1], 0x18000
	s_waitcnt lgkmcnt(0)
	v_mul_f32_e32 v3, v12, v2
	s_nop 1
	v_mov_b32_dpp v4, v3 quad_perm:[1,0,3,2] row_mask:0xf bank_mask:0xf
	v_lshl_add_u64 v[0:1], v[0:1], 0, s[0:1]
	s_and_saveexec_b64 s[4:5], vcc
	s_cbranch_execz .LBB0_1233
	s_waitcnt lgkmcnt(0)
	v_cvt_pk_bf16_f32 v3, v3, v4
	global_store_dword v[0:1], v3, off offset:3072
.LBB0_1233:
	s_or_b64 exec, exec, s[4:5]
	v_mul_f32_e32 v3, v28, v2
	s_waitcnt lgkmcnt(0)
	s_nop 1
	v_mov_b32_dpp v4, v3 quad_perm:[1,0,3,2] row_mask:0xf bank_mask:0xf
	s_and_saveexec_b64 s[4:5], vcc
	s_cbranch_execz .LBB0_1235
	s_waitcnt lgkmcnt(0)
	v_cvt_pk_bf16_f32 v3, v3, v4
	global_store_dword v[0:1], v3, off offset:3136
.LBB0_1235:
	s_or_b64 exec, exec, s[4:5]
	v_mul_f32_e32 v3, v44, v2
	s_waitcnt lgkmcnt(0)
	s_nop 1
	v_mov_b32_dpp v4, v3 quad_perm:[1,0,3,2] row_mask:0xf bank_mask:0xf
	s_and_saveexec_b64 s[4:5], vcc
	s_cbranch_execz .LBB0_1237
	s_waitcnt lgkmcnt(0)
	v_cvt_pk_bf16_f32 v3, v3, v4
	global_store_dword v[0:1], v3, off offset:3200
.LBB0_1237:
	s_or_b64 exec, exec, s[4:5]
	v_mul_f32_e32 v2, v60, v2
	s_nop 1
	v_mov_b32_dpp v3, v2 quad_perm:[1,0,3,2] row_mask:0xf bank_mask:0xf
	s_and_saveexec_b64 s[4:5], vcc
	s_cbranch_execz .LBB0_1239
	s_waitcnt lgkmcnt(0)
	v_cvt_pk_bf16_f32 v2, v2, v3
	global_store_dword v[0:1], v2, off offset:3264
.LBB0_1239:
	s_or_b64 exec, exec, s[4:5]
	v_rcp_f32_e32 v2, v65
	v_lshlrev_b64 v[0:1], 12, v[164:165]
	v_lshl_add_u64 v[0:1], v[80:81], 0, v[0:1]
	s_mov_b64 s[0:1], 0x19000
	s_waitcnt lgkmcnt(0)
	v_mul_f32_e32 v3, v13, v2
	s_nop 1
	v_mov_b32_dpp v4, v3 quad_perm:[1,0,3,2] row_mask:0xf bank_mask:0xf
	v_lshl_add_u64 v[0:1], v[0:1], 0, s[0:1]
	s_and_saveexec_b64 s[4:5], vcc
	s_cbranch_execz .LBB0_1241
	s_waitcnt lgkmcnt(0)
	v_cvt_pk_bf16_f32 v3, v3, v4
	global_store_dword v[0:1], v3, off offset:3072
.LBB0_1241:
	s_or_b64 exec, exec, s[4:5]
	v_mul_f32_e32 v3, v29, v2
	s_waitcnt lgkmcnt(0)
	s_nop 1
	v_mov_b32_dpp v4, v3 quad_perm:[1,0,3,2] row_mask:0xf bank_mask:0xf
	s_and_saveexec_b64 s[4:5], vcc
	s_cbranch_execz .LBB0_1243
	s_waitcnt lgkmcnt(0)
	v_cvt_pk_bf16_f32 v3, v3, v4
	global_store_dword v[0:1], v3, off offset:3136
.LBB0_1243:
	s_or_b64 exec, exec, s[4:5]
	v_mul_f32_e32 v3, v45, v2
	s_waitcnt lgkmcnt(0)
	s_nop 1
	v_mov_b32_dpp v4, v3 quad_perm:[1,0,3,2] row_mask:0xf bank_mask:0xf
	s_and_saveexec_b64 s[4:5], vcc
	s_cbranch_execz .LBB0_1245
	s_waitcnt lgkmcnt(0)
	v_cvt_pk_bf16_f32 v3, v3, v4
	global_store_dword v[0:1], v3, off offset:3200
.LBB0_1245:
	s_or_b64 exec, exec, s[4:5]
	v_mul_f32_e32 v2, v61, v2
	s_nop 1
	v_mov_b32_dpp v3, v2 quad_perm:[1,0,3,2] row_mask:0xf bank_mask:0xf
	s_and_saveexec_b64 s[4:5], vcc
	s_cbranch_execz .LBB0_1247
	s_waitcnt lgkmcnt(0)
	v_cvt_pk_bf16_f32 v2, v2, v3
	global_store_dword v[0:1], v2, off offset:3264
.LBB0_1247:
	s_or_b64 exec, exec, s[4:5]
	v_rcp_f32_e32 v2, v66
	v_lshlrev_b64 v[0:1], 12, v[164:165]
	v_lshl_add_u64 v[0:1], v[80:81], 0, v[0:1]
	v_lshl_add_u64 v[0:1], v[0:1], 0, s[66:67]
	s_waitcnt lgkmcnt(0)
	v_mul_f32_e32 v3, v14, v2
	s_nop 1
	v_mov_b32_dpp v4, v3 quad_perm:[1,0,3,2] row_mask:0xf bank_mask:0xf
	s_and_saveexec_b64 s[4:5], vcc
	s_cbranch_execz .LBB0_1249
	s_waitcnt lgkmcnt(0)
	v_cvt_pk_bf16_f32 v3, v3, v4
	global_store_dword v[0:1], v3, off offset:3072
.LBB0_1249:
	s_or_b64 exec, exec, s[4:5]
	v_mul_f32_e32 v3, v30, v2
	s_waitcnt lgkmcnt(0)
	s_nop 1
	v_mov_b32_dpp v4, v3 quad_perm:[1,0,3,2] row_mask:0xf bank_mask:0xf
	s_and_saveexec_b64 s[4:5], vcc
	s_cbranch_execz .LBB0_1251
	s_waitcnt lgkmcnt(0)
	v_cvt_pk_bf16_f32 v3, v3, v4
	global_store_dword v[0:1], v3, off offset:3136
.LBB0_1251:
	s_or_b64 exec, exec, s[4:5]
	v_mul_f32_e32 v3, v46, v2
	s_waitcnt lgkmcnt(0)
	s_nop 1
	v_mov_b32_dpp v4, v3 quad_perm:[1,0,3,2] row_mask:0xf bank_mask:0xf
	s_and_saveexec_b64 s[4:5], vcc
	s_cbranch_execz .LBB0_1253
	s_waitcnt lgkmcnt(0)
	v_cvt_pk_bf16_f32 v3, v3, v4
	global_store_dword v[0:1], v3, off offset:3200
.LBB0_1253:
	s_or_b64 exec, exec, s[4:5]
	v_mul_f32_e32 v2, v62, v2
	s_nop 1
	v_mov_b32_dpp v3, v2 quad_perm:[1,0,3,2] row_mask:0xf bank_mask:0xf
	s_and_saveexec_b64 s[4:5], vcc
	s_cbranch_execz .LBB0_1255
	s_waitcnt lgkmcnt(0)
	v_cvt_pk_bf16_f32 v2, v2, v3
	global_store_dword v[0:1], v2, off offset:3264
.LBB0_1255:
	s_or_b64 exec, exec, s[4:5]
	v_rcp_f32_e32 v2, v67
	v_lshlrev_b64 v[0:1], 12, v[164:165]
	v_lshl_add_u64 v[0:1], v[80:81], 0, v[0:1]
	v_lshl_add_u64 v[0:1], v[0:1], 0, s[68:69]
	s_waitcnt lgkmcnt(0)
	v_mul_f32_e32 v3, v15, v2
	s_nop 1
	v_mov_b32_dpp v4, v3 quad_perm:[1,0,3,2] row_mask:0xf bank_mask:0xf
	s_and_saveexec_b64 s[4:5], vcc
	s_cbranch_execz .LBB0_1257
	s_waitcnt lgkmcnt(0)
	v_cvt_pk_bf16_f32 v3, v3, v4
	global_store_dword v[0:1], v3, off offset:3072
.LBB0_1257:
	s_or_b64 exec, exec, s[4:5]
	v_mul_f32_e32 v3, v31, v2
	s_waitcnt lgkmcnt(0)
	s_nop 1
	v_mov_b32_dpp v4, v3 quad_perm:[1,0,3,2] row_mask:0xf bank_mask:0xf
	s_and_saveexec_b64 s[4:5], vcc
	s_cbranch_execz .LBB0_1259
	s_waitcnt lgkmcnt(0)
	v_cvt_pk_bf16_f32 v3, v3, v4
	global_store_dword v[0:1], v3, off offset:3136
.LBB0_1259:
	s_or_b64 exec, exec, s[4:5]
	v_mul_f32_e32 v3, v47, v2
	s_waitcnt lgkmcnt(0)
	s_nop 1
	v_mov_b32_dpp v4, v3 quad_perm:[1,0,3,2] row_mask:0xf bank_mask:0xf
	s_and_saveexec_b64 s[4:5], vcc
	s_cbranch_execz .LBB0_1261
	s_waitcnt lgkmcnt(0)
	v_cvt_pk_bf16_f32 v3, v3, v4
	global_store_dword v[0:1], v3, off offset:3200
.LBB0_1261:
	s_or_b64 exec, exec, s[4:5]
	v_mul_f32_e32 v2, v63, v2
	s_nop 1
	v_mov_b32_dpp v3, v2 quad_perm:[1,0,3,2] row_mask:0xf bank_mask:0xf
	s_and_saveexec_b64 s[4:5], vcc
	s_cbranch_execz .LBB0_837
	s_waitcnt lgkmcnt(0)
	v_cvt_pk_bf16_f32 v2, v2, v3
	global_store_dword v[0:1], v2, off offset:3264
	s_branch .LBB0_837
